# phase0 convT load batching extended to all 10 instances (WQ, WKV, WBR x3, WOUT added)
# speedup vs baseline: 1.0090x; 1.0030x over previous
; template <class F>
; DI void convT(bf16* dst, int N, int K, const float* src, const float* src2, int ld, const float* gain, F cmap, bf16* tile) {
;     ...
;     for (int e = tid; e < 4096; e += NTHR) {
;       const int kk = e >> 6, nn = e & 63;
;       const int k = tk * 64 + kk, n = tn * 64 + nn;
;       const int sc = cmap(n);
;       float v = 0.f;
;       if (sc >= 0) {
;         const float* s = (sc & (1 << 28)) ? src2 : src;
;         v = s[(size_t)k * ld + (sc & ((1 << 28) - 1))];
;         if (gain) v *= gain[k];
;       }
;       tile[nn * 66 + kk] = f2bf(v);
;     }
.LBB0_48:
	s_mul_hi_i32 s52, s59, 0x2aaaaaab
	s_lshr_b32 s53, s52, 31
	s_ashr_i32 s67, s52, 1
	s_add_i32 s67, s67, s53
	s_mul_i32 s52, s67, 12
	s_sub_i32 s66, s59, s52
	s_and_saveexec_b64 s[52:53], s[0:1]
	s_cbranch_execz .LBB0_55
	s_cmp_gt_i32 s66, -1
	s_cselect_b64 s[54:55], -1, 0
	s_lshl_b32 s56, s66, 6
	s_and_b32 s56, s56, 0xfffffc0
	v_or_b32_e32 v4, s56, v13
	v_lshlrev_b32_e32 v8, 2, v4
	s_lshl_b32 s68, s67, 6
	v_lshl_add_u64 v[4:5], s[8:9], 0, v[8:9]
	s_mov_b64 s[56:57], 0
	s_movk_i32 s69, 0xc00
	v_ashrrev_i32_e32 v14, 6, v0
	v_mov_b32_e32 v230, 0
	v_mov_b32_e32 v231, 0
	v_mov_b32_e32 v232, 0
	v_mov_b32_e32 v233, 0
	v_mov_b32_e32 v234, 0
	v_mov_b32_e32 v235, 0
	v_mov_b32_e32 v236, 0
	v_mov_b32_e32 v237, 0
	s_andn2_b64 vcc, exec, s[54:55]
	s_cbranch_vccnz .Lcvb9_e
	v_add_u32_e32 v6, s68, v14
	v_mad_i64_i32 v[20:21], s[70:71], v6, s69, v[4:5]
	global_load_dword v230, v[20:21], off
	v_add_u32_e32 v6, 8, v6
	v_mad_i64_i32 v[20:21], s[70:71], v6, s69, v[4:5]
	global_load_dword v231, v[20:21], off
	v_add_u32_e32 v6, 8, v6
	v_mad_i64_i32 v[20:21], s[70:71], v6, s69, v[4:5]
	global_load_dword v232, v[20:21], off
	v_add_u32_e32 v6, 8, v6
	v_mad_i64_i32 v[20:21], s[70:71], v6, s69, v[4:5]
	global_load_dword v233, v[20:21], off
	v_add_u32_e32 v6, 8, v6
	v_mad_i64_i32 v[20:21], s[70:71], v6, s69, v[4:5]
	global_load_dword v234, v[20:21], off
	v_add_u32_e32 v6, 8, v6
	v_mad_i64_i32 v[20:21], s[70:71], v6, s69, v[4:5]
	global_load_dword v235, v[20:21], off
	v_add_u32_e32 v6, 8, v6
	v_mad_i64_i32 v[20:21], s[70:71], v6, s69, v[4:5]
	global_load_dword v236, v[20:21], off
	v_add_u32_e32 v6, 8, v6
	v_mad_i64_i32 v[20:21], s[70:71], v6, s69, v[4:5]
	global_load_dword v237, v[20:21], off
	s_andn2_b64 vcc, exec, s[38:39]
	s_cbranch_vccnz .Lcvb9_e
	v_add_u32_e32 v6, s68, v14
	v_ashrrev_i32_e32 v7, 31, v6
	v_lshl_add_u64 v[6:7], v[6:7], 2, s[50:51]
	global_load_dword v238, v[6:7], off
	global_load_dword v239, v[6:7], off offset:32
	global_load_dword v240, v[6:7], off offset:64
	global_load_dword v241, v[6:7], off offset:96
	global_load_dword v242, v[6:7], off offset:128
	global_load_dword v243, v[6:7], off offset:160
	global_load_dword v244, v[6:7], off offset:192
	global_load_dword v245, v[6:7], off offset:224
	s_waitcnt vmcnt(0)
	v_mul_f32_e32 v230, v230, v238
	v_mul_f32_e32 v231, v231, v239
	v_mul_f32_e32 v232, v232, v240
	v_mul_f32_e32 v233, v233, v241
	v_mul_f32_e32 v234, v234, v242
	v_mul_f32_e32 v235, v235, v243
	v_mul_f32_e32 v236, v236, v244
	v_mul_f32_e32 v237, v237, v245
.Lcvb9_e:
	s_waitcnt vmcnt(0)
	v_lshl_add_u32 v7, v14, 1, v17
	v_cvt_pk_bf16_f32 v230, v230, s0
	v_cvt_pk_bf16_f32 v231, v231, s0
	v_cvt_pk_bf16_f32 v232, v232, s0
	v_cvt_pk_bf16_f32 v233, v233, s0
	v_cvt_pk_bf16_f32 v234, v234, s0
	v_cvt_pk_bf16_f32 v235, v235, s0
	v_cvt_pk_bf16_f32 v236, v236, s0
	v_cvt_pk_bf16_f32 v237, v237, s0
	ds_write_b16 v7, v230
	ds_write_b16 v7, v231 offset:16
	ds_write_b16 v7, v232 offset:32
	ds_write_b16 v7, v233 offset:48
	ds_write_b16 v7, v234 offset:64
	ds_write_b16 v7, v235 offset:80
	ds_write_b16 v7, v236 offset:96
	ds_write_b16 v7, v237 offset:112

; template <class F>
; DI void convT(bf16* dst, int N, int K, const float* src, const float* src2, int ld, const float* gain, F cmap, bf16* tile) {
;     ...
;     for (int e = tid; e < 4096; e += NTHR) {
;       const int kk = e >> 6, nn = e & 63;
;       const int k = tk * 64 + kk, n = tn * 64 + nn;
;       const int sc = cmap(n);
;       float v = 0.f;
;       if (sc >= 0) {
;         const float* s = (sc & (1 << 28)) ? src2 : src;
;         v = s[(size_t)k * ld + (sc & ((1 << 28) - 1))];
;         if (gain) v *= gain[k];
;       }
;       tile[nn * 66 + kk] = f2bf(v);
;     }
.LBB0_68:
	s_ashr_i32 s52, s59, 31
	s_lshr_b32 s52, s52, 28
	s_add_i32 s52, s59, s52
	s_ashr_i32 s67, s52, 4
	s_and_b32 s52, s52, -16
	s_sub_i32 s66, s59, s52
	s_and_saveexec_b64 s[52:53], s[0:1]
	s_cbranch_execz .LBB0_75
	s_cmp_gt_i32 s66, -1
	s_cselect_b64 s[54:55], -1, 0
	s_lshl_b32 s56, s66, 6
	s_and_b32 s56, s56, 0xfffffc0
	v_or_b32_e32 v4, s56, v13
	v_lshlrev_b32_e32 v8, 2, v4
	s_lshl_b32 s68, s67, 6
	v_lshl_add_u64 v[4:5], s[8:9], 0, v[8:9]
	s_mov_b64 s[56:57], 0
	v_ashrrev_i32_e32 v14, 6, v0
	v_mov_b32_e32 v230, 0
	v_mov_b32_e32 v231, 0
	v_mov_b32_e32 v232, 0
	v_mov_b32_e32 v233, 0
	v_mov_b32_e32 v234, 0
	v_mov_b32_e32 v235, 0
	v_mov_b32_e32 v236, 0
	v_mov_b32_e32 v237, 0
	s_andn2_b64 vcc, exec, s[54:55]
	s_cbranch_vccnz .LcvbA_e
	v_add_u32_e32 v6, s68, v14
	v_ashrrev_i32_e32 v7, 31, v6
	v_lshlrev_b64 v[20:21], 12, v[6:7]
	v_lshl_add_u64 v[20:21], v[4:5], 0, v[20:21]
	global_load_dword v230, v[20:21], off
	v_add_u32_e32 v6, 8, v6
	v_ashrrev_i32_e32 v7, 31, v6
	v_lshlrev_b64 v[20:21], 12, v[6:7]
	v_lshl_add_u64 v[20:21], v[4:5], 0, v[20:21]
	global_load_dword v231, v[20:21], off
	v_add_u32_e32 v6, 8, v6
	v_ashrrev_i32_e32 v7, 31, v6
	v_lshlrev_b64 v[20:21], 12, v[6:7]
	v_lshl_add_u64 v[20:21], v[4:5], 0, v[20:21]
	global_load_dword v232, v[20:21], off
	v_add_u32_e32 v6, 8, v6
	v_ashrrev_i32_e32 v7, 31, v6
	v_lshlrev_b64 v[20:21], 12, v[6:7]
	v_lshl_add_u64 v[20:21], v[4:5], 0, v[20:21]
	global_load_dword v233, v[20:21], off
	v_add_u32_e32 v6, 8, v6
	v_ashrrev_i32_e32 v7, 31, v6
	v_lshlrev_b64 v[20:21], 12, v[6:7]
	v_lshl_add_u64 v[20:21], v[4:5], 0, v[20:21]
	global_load_dword v234, v[20:21], off
	v_add_u32_e32 v6, 8, v6
	v_ashrrev_i32_e32 v7, 31, v6
	v_lshlrev_b64 v[20:21], 12, v[6:7]
	v_lshl_add_u64 v[20:21], v[4:5], 0, v[20:21]
	global_load_dword v235, v[20:21], off
	v_add_u32_e32 v6, 8, v6
	v_ashrrev_i32_e32 v7, 31, v6
	v_lshlrev_b64 v[20:21], 12, v[6:7]
	v_lshl_add_u64 v[20:21], v[4:5], 0, v[20:21]
	global_load_dword v236, v[20:21], off
	v_add_u32_e32 v6, 8, v6
	v_ashrrev_i32_e32 v7, 31, v6
	v_lshlrev_b64 v[20:21], 12, v[6:7]
	v_lshl_add_u64 v[20:21], v[4:5], 0, v[20:21]
	global_load_dword v237, v[20:21], off
	s_andn2_b64 vcc, exec, s[40:41]
	s_cbranch_vccnz .LcvbA_e
	v_add_u32_e32 v6, s68, v14
	v_ashrrev_i32_e32 v7, 31, v6
	v_lshl_add_u64 v[6:7], v[6:7], 2, s[50:51]
	global_load_dword v238, v[6:7], off
	global_load_dword v239, v[6:7], off offset:32
	global_load_dword v240, v[6:7], off offset:64
	global_load_dword v241, v[6:7], off offset:96
	global_load_dword v242, v[6:7], off offset:128
	global_load_dword v243, v[6:7], off offset:160
	global_load_dword v244, v[6:7], off offset:192
	global_load_dword v245, v[6:7], off offset:224
	s_waitcnt vmcnt(0)
	v_mul_f32_e32 v230, v230, v238
	v_mul_f32_e32 v231, v231, v239
	v_mul_f32_e32 v232, v232, v240
	v_mul_f32_e32 v233, v233, v241
	v_mul_f32_e32 v234, v234, v242
	v_mul_f32_e32 v235, v235, v243
	v_mul_f32_e32 v236, v236, v244
	v_mul_f32_e32 v237, v237, v245

; template <class F>
; DI void convT(bf16* dst, int N, int K, const float* src, const float* src2, int ld, const float* gain, F cmap, bf16* tile) {
;     ...
;     for (int e = tid; e < 4096; e += NTHR) {
;       const int kk = e >> 6, nn = e & 63;
;       const int k = tk * 64 + kk, n = tn * 64 + nn;
;       const int sc = cmap(n);
;       float v = 0.f;
;       if (sc >= 0) {
;         const float* s = (sc & (1 << 28)) ? src2 : src;
;         v = s[(size_t)k * ld + (sc & ((1 << 28) - 1))];
;         if (gain) v *= gain[k];
;       }
;       tile[nn * 66 + kk] = f2bf(v);
;     }
;     __syncthreads();
;     for (int e = tid; e < 4096; e += NTHR) {
;       const int nn = e >> 6, kk = e & 63;
;       dst[(size_t)(tn * 64 + nn) * K + tk * 64 + kk] = tile[nn * 66 + kk];
;     }
.LBB0_88:
	s_ashr_i32 s8, s57, 31
	s_lshr_b32 s8, s8, 28
	s_add_i32 s8, s57, s8
	s_ashr_i32 s59, s8, 4
	s_and_b32 s8, s8, -16
	s_sub_i32 s58, s57, s8
	s_and_saveexec_b64 s[8:9], s[0:1]
	s_cbranch_execz .LBB0_94
	s_cmp_gt_i32 s58, -1
	s_cselect_b64 s[52:53], -1, 0
	s_lshl_b32 s54, s58, 6
	s_and_b32 s54, s54, 0xfffffc0
	v_or_b32_e32 v4, s54, v13
	v_lshlrev_b32_e32 v8, 2, v4
	s_lshl_b32 s66, s59, 6
	v_lshl_add_u64 v[4:5], s[50:51], 0, v[8:9]
	s_mov_b64 s[54:55], 0
	v_ashrrev_i32_e32 v7, 6, v0
	v_mov_b32_e32 v230, 0
	v_mov_b32_e32 v231, 0
	v_mov_b32_e32 v232, 0
	v_mov_b32_e32 v233, 0
	v_mov_b32_e32 v234, 0
	v_mov_b32_e32 v235, 0
	v_mov_b32_e32 v236, 0
	v_mov_b32_e32 v237, 0
	s_andn2_b64 vcc, exec, s[52:53]
	s_cbranch_vccnz .Lcvb5_e
	v_add_u32_e32 v6, s66, v7
	v_ashrrev_i32_e32 v15, 31, v6
	v_mov_b32_e32 v14, v6
	v_lshlrev_b64 v[14:15], 12, v[14:15]
	v_lshl_add_u64 v[14:15], v[4:5], 0, v[14:15]
	global_load_dword v230, v[14:15], off
	v_add_u32_e32 v6, 8, v6
	v_ashrrev_i32_e32 v15, 31, v6
	v_mov_b32_e32 v14, v6
	v_lshlrev_b64 v[14:15], 12, v[14:15]
	v_lshl_add_u64 v[14:15], v[4:5], 0, v[14:15]
	global_load_dword v231, v[14:15], off
	v_add_u32_e32 v6, 8, v6
	v_ashrrev_i32_e32 v15, 31, v6
	v_mov_b32_e32 v14, v6
	v_lshlrev_b64 v[14:15], 12, v[14:15]
	v_lshl_add_u64 v[14:15], v[4:5], 0, v[14:15]
	global_load_dword v232, v[14:15], off
	v_add_u32_e32 v6, 8, v6
	v_ashrrev_i32_e32 v15, 31, v6
	v_mov_b32_e32 v14, v6
	v_lshlrev_b64 v[14:15], 12, v[14:15]
	v_lshl_add_u64 v[14:15], v[4:5], 0, v[14:15]
	global_load_dword v233, v[14:15], off
	v_add_u32_e32 v6, 8, v6
	v_ashrrev_i32_e32 v15, 31, v6
	v_mov_b32_e32 v14, v6
	v_lshlrev_b64 v[14:15], 12, v[14:15]
	v_lshl_add_u64 v[14:15], v[4:5], 0, v[14:15]
	global_load_dword v234, v[14:15], off
	v_add_u32_e32 v6, 8, v6
	v_ashrrev_i32_e32 v15, 31, v6
	v_mov_b32_e32 v14, v6
	v_lshlrev_b64 v[14:15], 12, v[14:15]
	v_lshl_add_u64 v[14:15], v[4:5], 0, v[14:15]
	global_load_dword v235, v[14:15], off
	v_add_u32_e32 v6, 8, v6
	v_ashrrev_i32_e32 v15, 31, v6
	v_mov_b32_e32 v14, v6
	v_lshlrev_b64 v[14:15], 12, v[14:15]
	v_lshl_add_u64 v[14:15], v[4:5], 0, v[14:15]
	global_load_dword v236, v[14:15], off
	v_add_u32_e32 v6, 8, v6
	v_ashrrev_i32_e32 v15, 31, v6
	v_mov_b32_e32 v14, v6
	v_lshlrev_b64 v[14:15], 12, v[14:15]
	v_lshl_add_u64 v[14:15], v[4:5], 0, v[14:15]
	global_load_dword v237, v[14:15], off
.Lcvb5_e:
	s_waitcnt vmcnt(0)
	v_lshl_add_u32 v7, v7, 1, v17
	v_cvt_pk_bf16_f32 v230, v230, s0
	v_cvt_pk_bf16_f32 v231, v231, s0
	v_cvt_pk_bf16_f32 v232, v232, s0
	v_cvt_pk_bf16_f32 v233, v233, s0
	v_cvt_pk_bf16_f32 v234, v234, s0
	v_cvt_pk_bf16_f32 v235, v235, s0
	v_cvt_pk_bf16_f32 v236, v236, s0
	v_cvt_pk_bf16_f32 v237, v237, s0
	ds_write_b16 v7, v230
	ds_write_b16 v7, v231 offset:16
	ds_write_b16 v7, v232 offset:32
	ds_write_b16 v7, v233 offset:48
	ds_write_b16 v7, v234 offset:64
	ds_write_b16 v7, v235 offset:80
	ds_write_b16 v7, v236 offset:96
	ds_write_b16 v7, v237 offset:112
.LBB0_94:
	s_or_b64 exec, exec, s[8:9]
	s_waitcnt lgkmcnt(0)
	s_barrier
	s_and_saveexec_b64 s[8:9], s[0:1]
	s_cbranch_execz .LBB0_87
	s_lshl_b32 s52, s59, 6
	s_ashr_i32 s53, s52, 31
	s_lshl_b32 s58, s58, 6
	v_lshl_add_u64 v[14:15], s[52:53], 1, v[10:11]
	s_mov_b64 s[54:55], -1
	v_mov_b32_e32 v4, v0
	s_and_saveexec_b64 s[52:53], s[4:5]
	s_cbranch_execz .LBB0_100
	v_mov_b64_e32 v[6:7], v[2:3]
	s_mov_b32 s59, s58
	s_mov_b32 s66, s58
	s_mov_b32 s67, s58
	s_mov_b64 s[54:55], 0
	v_mov_b32_e32 v8, v18
	v_mov_b64_e32 v[4:5], v[0:1]

; template <class F>
; DI void convT(bf16* dst, int N, int K, const float* src, const float* src2, int ld, const float* gain, F cmap, bf16* tile) {
;     ...
;     for (int e = tid; e < 4096; e += NTHR) {
;       const int kk = e >> 6, nn = e & 63;
;       const int k = tk * 64 + kk, n = tn * 64 + nn;
;       const int sc = cmap(n);
;       float v = 0.f;
;       if (sc >= 0) {
;         const float* s = (sc & (1 << 28)) ? src2 : src;
;         v = s[(size_t)k * ld + (sc & ((1 << 28) - 1))];
;         if (gain) v *= gain[k];
;       }
;       tile[nn * 66 + kk] = f2bf(v);
;     }
;     __syncthreads();
;     for (int e = tid; e < 4096; e += NTHR) {
;       const int nn = e >> 6, kk = e & 63;
;       dst[(size_t)(tn * 64 + nn) * K + tk * 64 + kk] = tile[nn * 66 + kk];
;     }
.LBB0_106:
	s_ashr_i32 s54, s67, 31
	s_lshr_b32 s54, s54, 28
	s_add_i32 s54, s67, s54
	s_ashr_i32 s69, s54, 4
	s_and_b32 s54, s54, -16
	s_sub_i32 s68, s67, s54
	s_and_saveexec_b64 s[54:55], s[4:5]
	s_cbranch_execz .LBB0_112
	s_cmp_gt_i32 s68, -1
	s_cselect_b64 s[56:57], -1, 0
	s_lshl_b32 s58, s68, 6
	s_and_b32 s58, s58, 0xfffffc0
	v_or_b32_e32 v4, s58, v13
	v_lshlrev_b32_e32 v8, 2, v4
	s_lshl_b32 s70, s69, 6
	v_lshl_add_u64 v[4:5], s[52:53], 0, v[8:9]
	s_mov_b64 s[58:59], 0
	v_ashrrev_i32_e32 v7, 6, v0
	v_mov_b32_e32 v230, 0
	v_mov_b32_e32 v231, 0
	v_mov_b32_e32 v232, 0
	v_mov_b32_e32 v233, 0
	v_mov_b32_e32 v234, 0
	v_mov_b32_e32 v235, 0
	v_mov_b32_e32 v236, 0
	v_mov_b32_e32 v237, 0
	s_andn2_b64 vcc, exec, s[56:57]
	s_cbranch_vccnz .Lcvb6_e
	v_add_u32_e32 v6, s70, v7
	v_ashrrev_i32_e32 v15, 31, v6
	v_mov_b32_e32 v14, v6
	v_lshlrev_b64 v[14:15], 12, v[14:15]
	v_lshl_add_u64 v[14:15], v[4:5], 0, v[14:15]
	global_load_dword v230, v[14:15], off
	v_add_u32_e32 v6, 8, v6
	v_ashrrev_i32_e32 v15, 31, v6
	v_mov_b32_e32 v14, v6
	v_lshlrev_b64 v[14:15], 12, v[14:15]
	v_lshl_add_u64 v[14:15], v[4:5], 0, v[14:15]
	global_load_dword v231, v[14:15], off
	v_add_u32_e32 v6, 8, v6
	v_ashrrev_i32_e32 v15, 31, v6
	v_mov_b32_e32 v14, v6
	v_lshlrev_b64 v[14:15], 12, v[14:15]
	v_lshl_add_u64 v[14:15], v[4:5], 0, v[14:15]
	global_load_dword v232, v[14:15], off
	v_add_u32_e32 v6, 8, v6
	v_ashrrev_i32_e32 v15, 31, v6
	v_mov_b32_e32 v14, v6
	v_lshlrev_b64 v[14:15], 12, v[14:15]
	v_lshl_add_u64 v[14:15], v[4:5], 0, v[14:15]
	global_load_dword v233, v[14:15], off
	v_add_u32_e32 v6, 8, v6
	v_ashrrev_i32_e32 v15, 31, v6
	v_mov_b32_e32 v14, v6
	v_lshlrev_b64 v[14:15], 12, v[14:15]
	v_lshl_add_u64 v[14:15], v[4:5], 0, v[14:15]
	global_load_dword v234, v[14:15], off
	v_add_u32_e32 v6, 8, v6
	v_ashrrev_i32_e32 v15, 31, v6
	v_mov_b32_e32 v14, v6
	v_lshlrev_b64 v[14:15], 12, v[14:15]
	v_lshl_add_u64 v[14:15], v[4:5], 0, v[14:15]
	global_load_dword v235, v[14:15], off
	v_add_u32_e32 v6, 8, v6
	v_ashrrev_i32_e32 v15, 31, v6
	v_mov_b32_e32 v14, v6
	v_lshlrev_b64 v[14:15], 12, v[14:15]
	v_lshl_add_u64 v[14:15], v[4:5], 0, v[14:15]
	global_load_dword v236, v[14:15], off
	v_add_u32_e32 v6, 8, v6
	v_ashrrev_i32_e32 v15, 31, v6
	v_mov_b32_e32 v14, v6
	v_lshlrev_b64 v[14:15], 12, v[14:15]
	v_lshl_add_u64 v[14:15], v[4:5], 0, v[14:15]
	global_load_dword v237, v[14:15], off
.Lcvb6_e:
	s_waitcnt vmcnt(0)
	v_lshl_add_u32 v7, v7, 1, v17
	v_cvt_pk_bf16_f32 v230, v230, s0
	v_cvt_pk_bf16_f32 v231, v231, s0
	v_cvt_pk_bf16_f32 v232, v232, s0
	v_cvt_pk_bf16_f32 v233, v233, s0
	v_cvt_pk_bf16_f32 v234, v234, s0
	v_cvt_pk_bf16_f32 v235, v235, s0
	v_cvt_pk_bf16_f32 v236, v236, s0
	v_cvt_pk_bf16_f32 v237, v237, s0
	ds_write_b16 v7, v230
	ds_write_b16 v7, v231 offset:16
	ds_write_b16 v7, v232 offset:32
	ds_write_b16 v7, v233 offset:48
	ds_write_b16 v7, v234 offset:64
	ds_write_b16 v7, v235 offset:80
	ds_write_b16 v7, v236 offset:96
	ds_write_b16 v7, v237 offset:112
.LBB0_112:
	s_or_b64 exec, exec, s[54:55]
	s_waitcnt lgkmcnt(0)
	s_barrier
	s_and_saveexec_b64 s[54:55], s[4:5]
	s_cbranch_execz .LBB0_105
	s_lshl_b32 s56, s69, 6
	s_ashr_i32 s57, s56, 31
	s_lshl_b32 s68, s68, 6
	v_lshl_add_u64 v[14:15], s[56:57], 1, v[10:11]
	s_mov_b64 s[58:59], -1
	v_mov_b32_e32 v4, v0
	s_and_saveexec_b64 s[56:57], s[6:7]
	s_cbranch_execz .LBB0_117
	v_mov_b64_e32 v[6:7], v[2:3]
	s_mov_b32 s69, s68
	s_mov_b32 s70, s68
	s_mov_b32 s71, s68
	s_mov_b64 s[58:59], 0
	v_mov_b32_e32 v8, v18
	v_mov_b64_e32 v[4:5], v[0:1]

; template <class F>
; DI void convT(bf16* dst, int N, int K, const float* src, const float* src2, int ld, const float* gain, F cmap, bf16* tile) {
;     ...
;     for (int e = tid; e < 4096; e += NTHR) {
;       const int kk = e >> 6, nn = e & 63;
;       const int k = tk * 64 + kk, n = tn * 64 + nn;
;       const int sc = cmap(n);
;       float v = 0.f;
;       if (sc >= 0) {
;         const float* s = (sc & (1 << 28)) ? src2 : src;
;         v = s[(size_t)k * ld + (sc & ((1 << 28) - 1))];
;         if (gain) v *= gain[k];
;       }
;       tile[nn * 66 + kk] = f2bf(v);
;     }
;     __syncthreads();
;     for (int e = tid; e < 4096; e += NTHR) {
;       const int nn = e >> 6, kk = e & 63;
;       dst[(size_t)(tn * 64 + nn) * K + tk * 64 + kk] = tile[nn * 66 + kk];
.LBB0_123:
	s_ashr_i32 s50, s57, 31
	s_lshr_b32 s50, s50, 28
	s_add_i32 s50, s57, s50
	s_ashr_i32 s59, s50, 4
	s_and_b32 s50, s50, -16
	s_sub_i32 s58, s57, s50
	s_and_saveexec_b64 s[50:51], s[0:1]
	s_cbranch_execz .LBB0_129
	s_cmp_gt_i32 s58, -1
	s_cselect_b64 s[52:53], -1, 0
	s_lshl_b32 s54, s58, 6
	s_and_b32 s54, s54, 0xfffffc0
	v_or_b32_e32 v4, s54, v13
	v_lshlrev_b32_e32 v8, 2, v4
	s_lshl_b32 s66, s59, 6
	v_lshl_add_u64 v[4:5], s[8:9], 0, v[8:9]
	s_mov_b64 s[54:55], 0
	v_ashrrev_i32_e32 v7, 6, v0
	v_mov_b32_e32 v230, 0
	v_mov_b32_e32 v231, 0
	v_mov_b32_e32 v232, 0
	v_mov_b32_e32 v233, 0
	v_mov_b32_e32 v234, 0
	v_mov_b32_e32 v235, 0
	v_mov_b32_e32 v236, 0
	v_mov_b32_e32 v237, 0
	s_andn2_b64 vcc, exec, s[52:53]
	s_cbranch_vccnz .Lcvb7_e
	v_add_u32_e32 v6, s66, v7
	v_ashrrev_i32_e32 v15, 31, v6
	v_mov_b32_e32 v14, v6
	v_lshlrev_b64 v[14:15], 12, v[14:15]
	v_lshl_add_u64 v[14:15], v[4:5], 0, v[14:15]
	global_load_dword v230, v[14:15], off
	v_add_u32_e32 v6, 8, v6
	v_ashrrev_i32_e32 v15, 31, v6
	v_mov_b32_e32 v14, v6
	v_lshlrev_b64 v[14:15], 12, v[14:15]
	v_lshl_add_u64 v[14:15], v[4:5], 0, v[14:15]
	global_load_dword v231, v[14:15], off
	v_add_u32_e32 v6, 8, v6
	v_ashrrev_i32_e32 v15, 31, v6
	v_mov_b32_e32 v14, v6
	v_lshlrev_b64 v[14:15], 12, v[14:15]
	v_lshl_add_u64 v[14:15], v[4:5], 0, v[14:15]
	global_load_dword v232, v[14:15], off
	v_add_u32_e32 v6, 8, v6
	v_ashrrev_i32_e32 v15, 31, v6
	v_mov_b32_e32 v14, v6
	v_lshlrev_b64 v[14:15], 12, v[14:15]
	v_lshl_add_u64 v[14:15], v[4:5], 0, v[14:15]
	global_load_dword v233, v[14:15], off
	v_add_u32_e32 v6, 8, v6
	v_ashrrev_i32_e32 v15, 31, v6
	v_mov_b32_e32 v14, v6
	v_lshlrev_b64 v[14:15], 12, v[14:15]
	v_lshl_add_u64 v[14:15], v[4:5], 0, v[14:15]
	global_load_dword v234, v[14:15], off
	v_add_u32_e32 v6, 8, v6
	v_ashrrev_i32_e32 v15, 31, v6
	v_mov_b32_e32 v14, v6
	v_lshlrev_b64 v[14:15], 12, v[14:15]
	v_lshl_add_u64 v[14:15], v[4:5], 0, v[14:15]
	global_load_dword v235, v[14:15], off
	v_add_u32_e32 v6, 8, v6
	v_ashrrev_i32_e32 v15, 31, v6
	v_mov_b32_e32 v14, v6
	v_lshlrev_b64 v[14:15], 12, v[14:15]
	v_lshl_add_u64 v[14:15], v[4:5], 0, v[14:15]
	global_load_dword v236, v[14:15], off
	v_add_u32_e32 v6, 8, v6
	v_ashrrev_i32_e32 v15, 31, v6
	v_mov_b32_e32 v14, v6
	v_lshlrev_b64 v[14:15], 12, v[14:15]
	v_lshl_add_u64 v[14:15], v[4:5], 0, v[14:15]
	global_load_dword v237, v[14:15], off
.Lcvb7_e:
	s_waitcnt vmcnt(0)
	v_lshl_add_u32 v7, v7, 1, v17
	v_cvt_pk_bf16_f32 v230, v230, s0
	v_cvt_pk_bf16_f32 v231, v231, s0
	v_cvt_pk_bf16_f32 v232, v232, s0
	v_cvt_pk_bf16_f32 v233, v233, s0
	v_cvt_pk_bf16_f32 v234, v234, s0
	v_cvt_pk_bf16_f32 v235, v235, s0
	v_cvt_pk_bf16_f32 v236, v236, s0
	v_cvt_pk_bf16_f32 v237, v237, s0
	ds_write_b16 v7, v230
	ds_write_b16 v7, v231 offset:16
	ds_write_b16 v7, v232 offset:32
	ds_write_b16 v7, v233 offset:48
	ds_write_b16 v7, v234 offset:64
	ds_write_b16 v7, v235 offset:80
	ds_write_b16 v7, v236 offset:96
	ds_write_b16 v7, v237 offset:112
.LBB0_129:
	s_or_b64 exec, exec, s[50:51]
	s_waitcnt lgkmcnt(0)
	s_barrier
	s_and_saveexec_b64 s[50:51], s[0:1]
	s_cbranch_execz .LBB0_122
	s_lshl_b32 s52, s59, 6
	s_ashr_i32 s53, s52, 31
	s_lshl_b32 s58, s58, 6
	v_lshl_add_u64 v[14:15], s[52:53], 1, v[10:11]
	s_mov_b64 s[54:55], -1
	v_mov_b32_e32 v4, v0
	s_and_saveexec_b64 s[52:53], s[4:5]
	s_cbranch_execz .LBB0_134
	v_mov_b64_e32 v[6:7], v[2:3]
	s_mov_b32 s59, s58
	s_mov_b32 s66, s58
	s_mov_b32 s67, s58
	s_mov_b64 s[54:55], 0
	v_mov_b32_e32 v8, v18
	v_mov_b64_e32 v[4:5], v[0:1]

; template <class F>
; DI void convT(bf16* dst, int N, int K, const float* src, const float* src2, int ld, const float* gain, F cmap, bf16* tile) {
;     ...
;     for (int e = tid; e < 4096; e += NTHR) {
;       const int kk = e >> 6, nn = e & 63;
;       const int k = tk * 64 + kk, n = tn * 64 + nn;
;       const int sc = cmap(n);
;       float v = 0.f;
;       if (sc >= 0) {
;         const float* s = (sc & (1 << 28)) ? src2 : src;
;         v = s[(size_t)k * ld + (sc & ((1 << 28) - 1))];
;         if (gain) v *= gain[k];
;       }
;       tile[nn * 66 + kk] = f2bf(v);
;     }
;     __syncthreads();
;     for (int e = tid; e < 4096; e += NTHR) {
;       const int nn = e >> 6, kk = e & 63;
;       dst[(size_t)(tn * 64 + nn) * K + tk * 64 + kk] = tile[nn * 66 + kk];
.Lcvb8_e:
	s_waitcnt vmcnt(0)
	v_lshl_add_u32 v7, v7, 1, v17
	v_cvt_pk_bf16_f32 v230, v230, s0
	v_cvt_pk_bf16_f32 v231, v231, s0
	v_cvt_pk_bf16_f32 v232, v232, s0
	v_cvt_pk_bf16_f32 v233, v233, s0
	v_cvt_pk_bf16_f32 v234, v234, s0
	v_cvt_pk_bf16_f32 v235, v235, s0
	v_cvt_pk_bf16_f32 v236, v236, s0
	v_cvt_pk_bf16_f32 v237, v237, s0
	ds_write_b16 v7, v230
	ds_write_b16 v7, v231 offset:16
	ds_write_b16 v7, v232 offset:32
	ds_write_b16 v7, v233 offset:48
	ds_write_b16 v7, v234 offset:64
	ds_write_b16 v7, v235 offset:80
	ds_write_b16 v7, v236 offset:96
	ds_write_b16 v7, v237 offset:112
.LBB0_146:
	s_or_b64 exec, exec, s[50:51]
	s_waitcnt lgkmcnt(0)
	s_barrier
	s_and_saveexec_b64 s[50:51], s[0:1]
	s_cbranch_execz .LBB0_139
	s_lshl_b32 s52, s59, 6
	s_ashr_i32 s53, s52, 31
	s_lshl_b32 s58, s58, 6
	v_lshl_add_u64 v[14:15], s[52:53], 1, v[10:11]
	s_mov_b64 s[54:55], -1
	v_mov_b32_e32 v4, v0
	s_and_saveexec_b64 s[52:53], s[4:5]
	s_cbranch_execz .LBB0_152
	v_mov_b64_e32 v[6:7], v[2:3]
	s_mov_b32 s59, s58
	s_mov_b32 s66, s58
	s_mov_b32 s67, s58
	s_mov_b64 s[54:55], 0
	v_mov_b32_e32 v8, v18
	v_mov_b64_e32 v[4:5], v[0:1]
